# phase-9 conversion split made grid-size robust (stride gridDim-128, fallback when gridDim<=128)
# baseline (speedup 1.0000x reference)
; DI void run_phase(const Params& P, int ph, unsigned char* shm, const int rep) {
;     ...
;     { int jlo = 0, jhi = 0, lw = l;
;       if (s == -1) { jhi = 10; } else if (s == 8) { jlo = 10; jhi = 13; } else if (s == 15 && more) { jhi = 10; lw = l + 1; }
;       if (jhi > jlo) convert_jobs(P, lw, jlo, jhi, shm); }
.LBB0_449:
	s_and_b64 s[0:1], s[58:59], s[60:61]
	s_and_b64 s[6:7], s[0:1], exec
	s_cselect_b32 s5, 10, 0
	s_mov_b32 s93, s2
	s_mov_b32 s94, s3
	s_mov_b32 s89, s75
	s_mov_b32 s90, s91
	s_and_b64 s[6:7], s[54:55], exec
	s_cselect_b32 s5, 10, s5
	v_writelane_b32 v242, s20, 36
	s_mov_b32 s20, 0
	s_cmp_lg_u32 s83, 9
	s_cbranch_scc1 .Lcvt_sel_done
	s_cmp_le_u32 s3, 0x80
	s_cbranch_scc1 .Lcvt_sel_all
	s_cmp_lt_u32 s2, 0x80
	s_cbranch_scc1 .Lcvt_sel_done
	s_sub_i32 s93, s2, 0x80
	s_sub_i32 s94, s3, 0x80
	s_lshl_b32 s89, s93, 6
	s_lshl_b32 s90, s94, 6
.Lcvt_sel_all:
	s_mov_b32 s5, 13
	s_mov_b32 s20, 10
